# GEMM K-loop heads aligned to 64 bytes (code placement only)
# baseline (speedup 1.0000x reference)
.LBB0_321:
	s_add_i32 s76, s71, -2
	s_add_u32 s82, s22, 0x100
	v_mov_b32_e32 v0, 0
	s_addc_u32 s83, s23, 0
	s_mov_b32 s24, 0
	s_waitcnt lgkmcnt(0)
	v_mov_b32_e32 v1, v0
	v_mov_b32_e32 v2, v0
	v_mov_b32_e32 v3, v0
	v_mov_b32_e32 v4, v0
	v_mov_b32_e32 v5, v0
	v_mov_b32_e32 v6, v0
	v_mov_b32_e32 v7, v0
	v_mov_b32_e32 v16, v0
	v_mov_b32_e32 v17, v0
	v_mov_b32_e32 v18, v0
	v_mov_b32_e32 v19, v0
	v_mov_b32_e32 v20, v0
	v_mov_b32_e32 v21, v0
	v_mov_b32_e32 v22, v0
	v_mov_b32_e32 v23, v0
	v_mov_b32_e32 v32, v0
	v_mov_b32_e32 v33, v0
	v_mov_b32_e32 v34, v0
	v_mov_b32_e32 v35, v0
	v_mov_b32_e32 v36, v0
	v_mov_b32_e32 v37, v0
	v_mov_b32_e32 v38, v0
	v_mov_b32_e32 v39, v0
	v_mov_b32_e32 v48, v0
	v_mov_b32_e32 v49, v0
	v_mov_b32_e32 v50, v0
	v_mov_b32_e32 v51, v0
	v_mov_b32_e32 v52, v0
	v_mov_b32_e32 v53, v0
	v_mov_b32_e32 v54, v0
	v_mov_b32_e32 v55, v0
	v_mov_b32_e32 v8, v0
	v_mov_b32_e32 v9, v0
	v_mov_b32_e32 v10, v0
	v_mov_b32_e32 v11, v0
	v_mov_b32_e32 v12, v0
	v_mov_b32_e32 v13, v0
	v_mov_b32_e32 v14, v0
	v_mov_b32_e32 v15, v0
	v_mov_b32_e32 v24, v0
	v_mov_b32_e32 v25, v0
	v_mov_b32_e32 v26, v0
	v_mov_b32_e32 v27, v0
	v_mov_b32_e32 v28, v0
	v_mov_b32_e32 v29, v0
	v_mov_b32_e32 v30, v0
	v_mov_b32_e32 v31, v0
	v_mov_b32_e32 v40, v0
	v_mov_b32_e32 v41, v0
	v_mov_b32_e32 v42, v0
	v_mov_b32_e32 v43, v0
	v_mov_b32_e32 v44, v0
	v_mov_b32_e32 v45, v0
	v_mov_b32_e32 v46, v0
	v_mov_b32_e32 v47, v0
	v_mov_b32_e32 v56, v0
	v_mov_b32_e32 v57, v0
	v_mov_b32_e32 v58, v0
	v_mov_b32_e32 v59, v0
	v_mov_b32_e32 v60, v0
	v_mov_b32_e32 v61, v0
	v_mov_b32_e32 v62, v0
	v_mov_b32_e32 v63, v0
	v_mov_b32_e32 v64, v0
	v_mov_b32_e32 v65, v0
	v_mov_b32_e32 v66, v0
	v_mov_b32_e32 v67, v0
	v_mov_b32_e32 v68, v0
	v_mov_b32_e32 v69, v0
	v_mov_b32_e32 v70, v0
	v_mov_b32_e32 v71, v0
	v_mov_b32_e32 v80, v0
	v_mov_b32_e32 v81, v0
	v_mov_b32_e32 v82, v0
	v_mov_b32_e32 v83, v0
	v_mov_b32_e32 v84, v0
	v_mov_b32_e32 v85, v0
	v_mov_b32_e32 v86, v0
	v_mov_b32_e32 v87, v0
	v_mov_b32_e32 v98, v0
	v_mov_b32_e32 v99, v0
	v_mov_b32_e32 v100, v0
	v_mov_b32_e32 v101, v0
	v_mov_b32_e32 v102, v0
	v_mov_b32_e32 v103, v0
	v_mov_b32_e32 v104, v0
	v_mov_b32_e32 v105, v0
	v_mov_b32_e32 v114, v0
	v_mov_b32_e32 v115, v0
	v_mov_b32_e32 v116, v0
	v_mov_b32_e32 v117, v0
	v_mov_b32_e32 v118, v0
	v_mov_b32_e32 v119, v0
	v_mov_b32_e32 v120, v0
	v_mov_b32_e32 v121, v0
	v_mov_b32_e32 v72, v0
	v_mov_b32_e32 v73, v0
	v_mov_b32_e32 v74, v0
	v_mov_b32_e32 v75, v0
	v_mov_b32_e32 v76, v0
	v_mov_b32_e32 v77, v0
	v_mov_b32_e32 v78, v0
	v_mov_b32_e32 v79, v0
	v_mov_b32_e32 v88, v0
	v_mov_b32_e32 v89, v0
	v_mov_b32_e32 v90, v0
	v_mov_b32_e32 v91, v0
	v_mov_b32_e32 v92, v0
	v_mov_b32_e32 v93, v0
	v_mov_b32_e32 v94, v0
	v_mov_b32_e32 v95, v0
	v_mov_b32_e32 v106, v0
	v_mov_b32_e32 v107, v0
	v_mov_b32_e32 v108, v0
	v_mov_b32_e32 v109, v0
	v_mov_b32_e32 v110, v0
	v_mov_b32_e32 v111, v0
	v_mov_b32_e32 v112, v0
	v_mov_b32_e32 v113, v0
	v_mov_b32_e32 v122, v0
	v_mov_b32_e32 v123, v0
	v_mov_b32_e32 v124, v0
	v_mov_b32_e32 v125, v0
	v_mov_b32_e32 v126, v0
	v_mov_b32_e32 v127, v0
	v_mov_b32_e32 v128, v0
	v_mov_b32_e32 v129, v0
	.p2align 6

.LBB0_375:
	s_ashr_i32 s17, s16, 31
	s_lshl_b64 s[18:19], s[16:17], 20
	s_add_u32 s18, s57, s18
	s_addc_u32 s19, s59, s19
	s_ashr_i32 s5, s4, 31
	s_lshl_b64 s[20:21], s[4:5], 20
	s_add_u32 s20, s38, s20
	s_addc_u32 s21, s55, s21
	s_cmp_lt_i32 s63, 1
	s_cbranch_scc1 .LBB0_379
	s_and_b64 s[24:25], s[22:23], exec
	s_cselect_b32 s5, s19, s11
	s_cselect_b32 s17, s18, s10
	s_cselect_b32 s70, s21, s7
	s_cselect_b32 s71, s20, s6
	s_add_i32 s76, s63, -2
	s_add_u32 s24, s10, 0x80080
	s_addc_u32 s25, s11, 0
	s_add_u32 s82, s6, 0x100
	s_addc_u32 s83, s7, 0
	s_mov_b32 s26, 0
	.p2align 6

.LBB0_602:
	s_ashr_i32 s17, s16, 31
	s_lshl_b64 s[18:19], s[16:17], 20
	s_add_u32 s18, s54, s18
	s_addc_u32 s19, s55, s19
	s_ashr_i32 s15, s14, 31
	s_lshl_b64 s[20:21], s[14:15], 20
	s_add_u32 s20, s38, s20
	s_addc_u32 s21, s56, s21
	s_cmp_lt_i32 s62, 1
	s_cbranch_scc1 .LBB0_606
	s_and_b64 s[24:25], s[22:23], exec
	s_cselect_b32 s15, s19, s11
	s_cselect_b32 s17, s18, s10
	s_cselect_b32 s64, s21, s5
	s_cselect_b32 s65, s20, s4
	s_add_i32 s66, s62, -2
	s_add_u32 s24, s10, 0x80080
	s_addc_u32 s25, s11, 0
	s_add_u32 s67, s4, 0x100
	s_addc_u32 s70, s5, 0
	s_mov_b32 s26, 0
	.p2align 6

.LBB0_1594:
	s_ashr_i32 s17, s16, 31
	s_lshl_b64 s[18:19], s[16:17], 18
	s_add_u32 s18, s4, s18
	s_addc_u32 s19, s5, s19
	s_ashr_i32 s15, s14, 31
	s_lshl_b64 s[20:21], s[14:15], 18
	s_add_u32 s20, s35, s20
	s_addc_u32 s21, s54, s21
	s_cmp_lt_i32 s65, 1
	s_cbranch_scc1 .LBB0_1602
	s_and_b64 s[26:27], s[0:1], exec
	s_cselect_b32 s15, s19, s23
	s_cselect_b32 s17, s18, s22
	s_cselect_b32 s66, s21, s25
	s_cselect_b32 s67, s20, s24
	s_add_i32 s70, s65, -2
	s_add_u32 s22, s22, 0x20080
	s_addc_u32 s23, s23, 0
	s_add_u32 s71, s24, 0x100
	v_mov_b32_e32 v0, 0
	s_addc_u32 s76, s25, 0
	s_mov_b32 s24, 0
	v_mov_b32_e32 v1, v0
	v_mov_b32_e32 v2, v0
	v_mov_b32_e32 v3, v0
	v_mov_b32_e32 v4, v0
	v_mov_b32_e32 v5, v0
	v_mov_b32_e32 v6, v0
	v_mov_b32_e32 v7, v0
	v_mov_b32_e32 v8, v0
	v_mov_b32_e32 v9, v0
	v_mov_b32_e32 v10, v0
	v_mov_b32_e32 v11, v0
	v_mov_b32_e32 v12, v0
	v_mov_b32_e32 v13, v0
	v_mov_b32_e32 v14, v0
	v_mov_b32_e32 v15, v0
	v_mov_b32_e32 v16, v0
	v_mov_b32_e32 v17, v0
	v_mov_b32_e32 v18, v0
	v_mov_b32_e32 v19, v0
	v_mov_b32_e32 v20, v0
	v_mov_b32_e32 v21, v0
	v_mov_b32_e32 v22, v0
	v_mov_b32_e32 v23, v0
	v_mov_b32_e32 v24, v0
	v_mov_b32_e32 v25, v0
	v_mov_b32_e32 v26, v0
	v_mov_b32_e32 v27, v0
	v_mov_b32_e32 v28, v0
	v_mov_b32_e32 v29, v0
	v_mov_b32_e32 v30, v0
	v_mov_b32_e32 v31, v0
	v_mov_b32_e32 v64, v0
	v_mov_b32_e32 v65, v0
	v_mov_b32_e32 v66, v0
	v_mov_b32_e32 v67, v0
	v_mov_b32_e32 v68, v0
	v_mov_b32_e32 v69, v0
	v_mov_b32_e32 v70, v0
	v_mov_b32_e32 v71, v0
	v_mov_b32_e32 v72, v0
	v_mov_b32_e32 v73, v0
	v_mov_b32_e32 v74, v0
	v_mov_b32_e32 v75, v0
	v_mov_b32_e32 v76, v0
	v_mov_b32_e32 v77, v0
	v_mov_b32_e32 v78, v0
	v_mov_b32_e32 v79, v0
	v_mov_b32_e32 v80, v0
	v_mov_b32_e32 v81, v0
	v_mov_b32_e32 v82, v0
	v_mov_b32_e32 v83, v0
	v_mov_b32_e32 v84, v0
	v_mov_b32_e32 v85, v0
	v_mov_b32_e32 v86, v0
	v_mov_b32_e32 v87, v0
	v_mov_b32_e32 v88, v0
	v_mov_b32_e32 v89, v0
	v_mov_b32_e32 v90, v0
	v_mov_b32_e32 v91, v0
	v_mov_b32_e32 v92, v0
	v_mov_b32_e32 v93, v0
	v_mov_b32_e32 v94, v0
	v_mov_b32_e32 v95, v0
	v_mov_b32_e32 v32, v0
	v_mov_b32_e32 v33, v0
	v_mov_b32_e32 v34, v0
	v_mov_b32_e32 v35, v0
	v_mov_b32_e32 v36, v0
	v_mov_b32_e32 v37, v0
	v_mov_b32_e32 v38, v0
	v_mov_b32_e32 v39, v0
	v_mov_b32_e32 v40, v0
	v_mov_b32_e32 v41, v0
	v_mov_b32_e32 v42, v0
	v_mov_b32_e32 v43, v0
	v_mov_b32_e32 v44, v0
	v_mov_b32_e32 v45, v0
	v_mov_b32_e32 v46, v0
	v_mov_b32_e32 v47, v0
	v_mov_b32_e32 v48, v0
	v_mov_b32_e32 v49, v0
	v_mov_b32_e32 v50, v0
	v_mov_b32_e32 v51, v0
	v_mov_b32_e32 v52, v0
	v_mov_b32_e32 v53, v0
	v_mov_b32_e32 v54, v0
	v_mov_b32_e32 v55, v0
	v_mov_b32_e32 v56, v0
	v_mov_b32_e32 v57, v0
	v_mov_b32_e32 v58, v0
	v_mov_b32_e32 v59, v0
	v_mov_b32_e32 v60, v0
	v_mov_b32_e32 v61, v0
	v_mov_b32_e32 v62, v0
	v_mov_b32_e32 v63, v0
	v_mov_b32_e32 v98, v0
	v_mov_b32_e32 v99, v0
	v_mov_b32_e32 v100, v0
	v_mov_b32_e32 v101, v0
	v_mov_b32_e32 v102, v0
	v_mov_b32_e32 v103, v0
	v_mov_b32_e32 v104, v0
	v_mov_b32_e32 v105, v0
	v_mov_b32_e32 v106, v0
	v_mov_b32_e32 v107, v0
	v_mov_b32_e32 v108, v0
	v_mov_b32_e32 v109, v0
	v_mov_b32_e32 v110, v0
	v_mov_b32_e32 v111, v0
	v_mov_b32_e32 v112, v0
	v_mov_b32_e32 v113, v0
	v_mov_b32_e32 v114, v0
	v_mov_b32_e32 v115, v0
	v_mov_b32_e32 v116, v0
	v_mov_b32_e32 v117, v0
	v_mov_b32_e32 v118, v0
	v_mov_b32_e32 v119, v0
	v_mov_b32_e32 v120, v0
	v_mov_b32_e32 v121, v0
	v_mov_b32_e32 v122, v0
	v_mov_b32_e32 v123, v0
	v_mov_b32_e32 v124, v0
	v_mov_b32_e32 v125, v0
	v_mov_b32_e32 v126, v0
	v_mov_b32_e32 v127, v0
	v_mov_b32_e32 v128, v0
	v_mov_b32_e32 v129, v0
	.p2align 6

.LBB0_1671:
	s_ashr_i32 s17, s16, 31
	s_lshl_b64 s[18:19], s[16:17], 20
	s_add_u32 s18, s1, s18
	s_addc_u32 s19, s28, s19
	s_ashr_i32 s15, s14, 31
	s_lshl_b64 s[20:21], s[14:15], 20
	s_add_u32 s20, s30, s20
	s_addc_u32 s21, s31, s21
	s_cmp_lt_i32 s65, 1
	s_cbranch_scc1 .LBB0_1695
	s_and_b64 s[26:27], s[4:5], exec
	s_cselect_b32 s15, s19, s23
	s_cselect_b32 s17, s18, s22
	s_cselect_b32 s66, s21, s25
	s_cselect_b32 s67, s20, s24
	s_add_i32 s70, s65, -2
	s_add_u32 s22, s22, 0x80080
	s_addc_u32 s23, s23, 0
	s_add_u32 s71, s24, 0x100
	v_mov_b32_e32 v0, 0
	s_addc_u32 s76, s25, 0
	s_mov_b32 s24, 0
	v_mov_b32_e32 v1, v0
	v_mov_b32_e32 v2, v0
	v_mov_b32_e32 v3, v0
	v_mov_b32_e32 v4, v0
	v_mov_b32_e32 v5, v0
	v_mov_b32_e32 v6, v0
	v_mov_b32_e32 v7, v0
	v_mov_b32_e32 v16, v0
	v_mov_b32_e32 v17, v0
	v_mov_b32_e32 v18, v0
	v_mov_b32_e32 v19, v0
	v_mov_b32_e32 v20, v0
	v_mov_b32_e32 v21, v0
	v_mov_b32_e32 v22, v0
	v_mov_b32_e32 v23, v0
	v_mov_b32_e32 v32, v0
	v_mov_b32_e32 v33, v0
	v_mov_b32_e32 v34, v0
	v_mov_b32_e32 v35, v0
	v_mov_b32_e32 v36, v0
	v_mov_b32_e32 v37, v0
	v_mov_b32_e32 v38, v0
	v_mov_b32_e32 v39, v0
	v_mov_b32_e32 v48, v0
	v_mov_b32_e32 v49, v0
	v_mov_b32_e32 v50, v0
	v_mov_b32_e32 v51, v0
	v_mov_b32_e32 v52, v0
	v_mov_b32_e32 v53, v0
	v_mov_b32_e32 v54, v0
	v_mov_b32_e32 v55, v0
	v_mov_b32_e32 v8, v0
	v_mov_b32_e32 v9, v0
	v_mov_b32_e32 v10, v0
	v_mov_b32_e32 v11, v0
	v_mov_b32_e32 v12, v0
	v_mov_b32_e32 v13, v0
	v_mov_b32_e32 v14, v0
	v_mov_b32_e32 v15, v0
	v_mov_b32_e32 v24, v0
	v_mov_b32_e32 v25, v0
	v_mov_b32_e32 v26, v0
	v_mov_b32_e32 v27, v0
	v_mov_b32_e32 v28, v0
	v_mov_b32_e32 v29, v0
	v_mov_b32_e32 v30, v0
	v_mov_b32_e32 v31, v0
	v_mov_b32_e32 v40, v0
	v_mov_b32_e32 v41, v0
	v_mov_b32_e32 v42, v0
	v_mov_b32_e32 v43, v0
	v_mov_b32_e32 v44, v0
	v_mov_b32_e32 v45, v0
	v_mov_b32_e32 v46, v0
	v_mov_b32_e32 v47, v0
	v_mov_b32_e32 v56, v0
	v_mov_b32_e32 v57, v0
	v_mov_b32_e32 v58, v0
	v_mov_b32_e32 v59, v0
	v_mov_b32_e32 v60, v0
	v_mov_b32_e32 v61, v0
	v_mov_b32_e32 v62, v0
	v_mov_b32_e32 v63, v0
	v_mov_b32_e32 v64, v0
	v_mov_b32_e32 v65, v0
	v_mov_b32_e32 v66, v0
	v_mov_b32_e32 v67, v0
	v_mov_b32_e32 v68, v0
	v_mov_b32_e32 v69, v0
	v_mov_b32_e32 v70, v0
	v_mov_b32_e32 v71, v0
	v_mov_b32_e32 v80, v0
	v_mov_b32_e32 v81, v0
	v_mov_b32_e32 v82, v0
	v_mov_b32_e32 v83, v0
	v_mov_b32_e32 v84, v0
	v_mov_b32_e32 v85, v0
	v_mov_b32_e32 v86, v0
	v_mov_b32_e32 v87, v0
	v_mov_b32_e32 v98, v0
	v_mov_b32_e32 v99, v0
	v_mov_b32_e32 v100, v0
	v_mov_b32_e32 v101, v0
	v_mov_b32_e32 v102, v0
	v_mov_b32_e32 v103, v0
	v_mov_b32_e32 v104, v0
	v_mov_b32_e32 v105, v0
	v_mov_b32_e32 v114, v0
	v_mov_b32_e32 v115, v0
	v_mov_b32_e32 v116, v0
	v_mov_b32_e32 v117, v0
	v_mov_b32_e32 v118, v0
	v_mov_b32_e32 v119, v0
	v_mov_b32_e32 v120, v0
	v_mov_b32_e32 v121, v0
	v_mov_b32_e32 v72, v0
	v_mov_b32_e32 v73, v0
	v_mov_b32_e32 v74, v0
	v_mov_b32_e32 v75, v0
	v_mov_b32_e32 v76, v0
	v_mov_b32_e32 v77, v0
	v_mov_b32_e32 v78, v0
	v_mov_b32_e32 v79, v0
	v_mov_b32_e32 v88, v0
	v_mov_b32_e32 v89, v0
	v_mov_b32_e32 v90, v0
	v_mov_b32_e32 v91, v0
	v_mov_b32_e32 v92, v0
	v_mov_b32_e32 v93, v0
	v_mov_b32_e32 v94, v0
	v_mov_b32_e32 v95, v0
	v_mov_b32_e32 v106, v0
	v_mov_b32_e32 v107, v0
	v_mov_b32_e32 v108, v0
	v_mov_b32_e32 v109, v0
	v_mov_b32_e32 v110, v0
	v_mov_b32_e32 v111, v0
	v_mov_b32_e32 v112, v0
	v_mov_b32_e32 v113, v0
	v_mov_b32_e32 v122, v0
	v_mov_b32_e32 v123, v0
	v_mov_b32_e32 v124, v0
	v_mov_b32_e32 v125, v0
	v_mov_b32_e32 v126, v0
	v_mov_b32_e32 v127, v0
	v_mov_b32_e32 v128, v0
	v_mov_b32_e32 v129, v0
	.p2align 6

.LBB0_1755:
	s_ashr_i32 s17, s16, 31
	s_lshl_b64 s[18:19], s[16:17], 20
	s_add_u32 s18, s0, s18
	s_addc_u32 s19, s1, s19
	s_ashr_i32 s15, s14, 31
	s_lshl_b64 s[20:21], s[14:15], 20
	s_add_u32 s20, s28, s20
	s_addc_u32 s21, s30, s21
	s_cmp_lt_i32 s61, 1
	s_cbranch_scc1 .LBB0_1779
	s_and_b64 s[26:27], s[12:13], exec
	s_cselect_b32 s15, s19, s23
	s_cselect_b32 s17, s18, s22
	s_cselect_b32 s62, s21, s25
	s_cselect_b32 s63, s20, s24
	s_add_i32 s64, s61, -2
	s_add_u32 s22, s22, 0x80080
	s_addc_u32 s23, s23, 0
	s_add_u32 s65, s24, 0x100
	v_mov_b32_e32 v0, 0
	s_addc_u32 s66, s25, 0
	s_mov_b32 s24, 0
	s_waitcnt lgkmcnt(0)
	v_mov_b32_e32 v1, v0
	v_mov_b32_e32 v2, v0
	v_mov_b32_e32 v3, v0
	v_mov_b32_e32 v4, v0
	v_mov_b32_e32 v5, v0
	v_mov_b32_e32 v6, v0
	v_mov_b32_e32 v7, v0
	v_mov_b32_e32 v16, v0
	v_mov_b32_e32 v17, v0
	v_mov_b32_e32 v18, v0
	v_mov_b32_e32 v19, v0
	v_mov_b32_e32 v20, v0
	v_mov_b32_e32 v21, v0
	v_mov_b32_e32 v22, v0
	v_mov_b32_e32 v23, v0
	v_mov_b32_e32 v32, v0
	v_mov_b32_e32 v33, v0
	v_mov_b32_e32 v34, v0
	v_mov_b32_e32 v35, v0
	v_mov_b32_e32 v36, v0
	v_mov_b32_e32 v37, v0
	v_mov_b32_e32 v38, v0
	v_mov_b32_e32 v39, v0
	v_mov_b32_e32 v48, v0
	v_mov_b32_e32 v49, v0
	v_mov_b32_e32 v50, v0
	v_mov_b32_e32 v51, v0
	v_mov_b32_e32 v52, v0
	v_mov_b32_e32 v53, v0
	v_mov_b32_e32 v54, v0
	v_mov_b32_e32 v55, v0
	v_mov_b32_e32 v8, v0
	v_mov_b32_e32 v9, v0
	v_mov_b32_e32 v10, v0
	v_mov_b32_e32 v11, v0
	v_mov_b32_e32 v12, v0
	v_mov_b32_e32 v13, v0
	v_mov_b32_e32 v14, v0
	v_mov_b32_e32 v15, v0
	v_mov_b32_e32 v24, v0
	v_mov_b32_e32 v25, v0
	v_mov_b32_e32 v26, v0
	v_mov_b32_e32 v27, v0
	v_mov_b32_e32 v28, v0
	v_mov_b32_e32 v29, v0
	v_mov_b32_e32 v30, v0
	v_mov_b32_e32 v31, v0
	v_mov_b32_e32 v40, v0
	v_mov_b32_e32 v41, v0
	v_mov_b32_e32 v42, v0
	v_mov_b32_e32 v43, v0
	v_mov_b32_e32 v44, v0
	v_mov_b32_e32 v45, v0
	v_mov_b32_e32 v46, v0
	v_mov_b32_e32 v47, v0
	v_mov_b32_e32 v56, v0
	v_mov_b32_e32 v57, v0
	v_mov_b32_e32 v58, v0
	v_mov_b32_e32 v59, v0
	v_mov_b32_e32 v60, v0
	v_mov_b32_e32 v61, v0
	v_mov_b32_e32 v62, v0
	v_mov_b32_e32 v63, v0
	v_mov_b32_e32 v64, v0
	v_mov_b32_e32 v65, v0
	v_mov_b32_e32 v66, v0
	v_mov_b32_e32 v67, v0
	v_mov_b32_e32 v68, v0
	v_mov_b32_e32 v69, v0
	v_mov_b32_e32 v70, v0
	v_mov_b32_e32 v71, v0
	v_mov_b32_e32 v80, v0
	v_mov_b32_e32 v81, v0
	v_mov_b32_e32 v82, v0
	v_mov_b32_e32 v83, v0
	v_mov_b32_e32 v84, v0
	v_mov_b32_e32 v85, v0
	v_mov_b32_e32 v86, v0
	v_mov_b32_e32 v87, v0
	v_mov_b32_e32 v98, v0
	v_mov_b32_e32 v99, v0
	v_mov_b32_e32 v100, v0
	v_mov_b32_e32 v101, v0
	v_mov_b32_e32 v102, v0
	v_mov_b32_e32 v103, v0
	v_mov_b32_e32 v104, v0
	v_mov_b32_e32 v105, v0
	v_mov_b32_e32 v114, v0
	v_mov_b32_e32 v115, v0
	v_mov_b32_e32 v116, v0
	v_mov_b32_e32 v117, v0
	v_mov_b32_e32 v118, v0
	v_mov_b32_e32 v119, v0
	v_mov_b32_e32 v120, v0
	v_mov_b32_e32 v121, v0
	v_mov_b32_e32 v72, v0
	v_mov_b32_e32 v73, v0
	v_mov_b32_e32 v74, v0
	v_mov_b32_e32 v75, v0
	v_mov_b32_e32 v76, v0
	v_mov_b32_e32 v77, v0
	v_mov_b32_e32 v78, v0
	v_mov_b32_e32 v79, v0
	v_mov_b32_e32 v88, v0
	v_mov_b32_e32 v89, v0
	v_mov_b32_e32 v90, v0
	v_mov_b32_e32 v91, v0
	v_mov_b32_e32 v92, v0
	v_mov_b32_e32 v93, v0
	v_mov_b32_e32 v94, v0
	v_mov_b32_e32 v95, v0
	v_mov_b32_e32 v106, v0
	v_mov_b32_e32 v107, v0
	v_mov_b32_e32 v108, v0
	v_mov_b32_e32 v109, v0
	v_mov_b32_e32 v110, v0
	v_mov_b32_e32 v111, v0
	v_mov_b32_e32 v112, v0
	v_mov_b32_e32 v113, v0
	v_mov_b32_e32 v122, v0
	v_mov_b32_e32 v123, v0
	v_mov_b32_e32 v124, v0
	v_mov_b32_e32 v125, v0
	v_mov_b32_e32 v126, v0
	v_mov_b32_e32 v127, v0
	v_mov_b32_e32 v128, v0
	v_mov_b32_e32 v129, v0
	.p2align 6

.LBB0_1793:
	s_ashr_i32 s71, s70, 31
	s_lshl_b64 s[6:7], s[70:71], 20
	s_add_u32 s82, s13, s6
	s_addc_u32 s83, s38, s7
	s_ashr_i32 s67, s66, 31
	s_lshl_b64 s[6:7], s[66:67], 20
	s_add_u32 s86, s76, s6
	s_addc_u32 s87, s92, s7
	s_cmp_lt_i32 s94, 1
	s_cbranch_scc1 .LBB0_1797
	s_and_b64 s[6:7], s[88:89], exec
	s_cselect_b32 s33, s83, s27
	s_cselect_b32 s61, s82, s26
	s_cselect_b32 s67, s87, s19
	s_cselect_b32 s71, s86, s18
	s_add_i32 s90, s94, -2
	s_add_u32 s6, s26, 0x80080
	s_addc_u32 s7, s27, 0
	s_add_u32 s91, s18, 0x100
	s_addc_u32 vcc_lo, s19, 0
	s_mov_b32 s8, 0
	.p2align 6

.LBB0_1910:
	s_ashr_i32 s65, s64, 31
	s_lshl_b64 s[6:7], s[64:65], 20
	s_add_u32 s70, s89, s6
	s_addc_u32 s71, s90, s7
	s_ashr_i32 s63, s62, 31
	s_lshl_b64 s[6:7], s[62:63], 20
	s_add_u32 s82, s91, s6
	s_addc_u32 s83, s92, s7
	s_cmp_lt_i32 s54, 1
	s_cbranch_scc1 .LBB0_1914
	s_and_b64 s[6:7], s[66:67], exec
	s_cselect_b32 s63, s71, s25
	s_cselect_b32 s65, s70, s24
	s_cselect_b32 s86, s83, s17
	s_cselect_b32 s87, s82, s16
	s_add_i32 vcc_lo, s54, -2
	s_add_u32 s6, s24, 0x80080
	s_addc_u32 s7, s25, 0
	s_add_u32 vcc_hi, s16, 0x100
	s_mov_b32 s46, s68
	s_addc_u32 s49, s17, 0
	s_mov_b32 s8, 0
	.p2align 6

.LBB0_2076:
	s_add_i32 s71, s70, -2
	s_add_u32 s76, s22, 0x100
	v_mov_b32_e32 v0, 0
	s_addc_u32 s82, s23, 0
	s_mov_b32 s24, 0
	v_mov_b32_e32 v1, v0
	v_mov_b32_e32 v2, v0
	v_mov_b32_e32 v3, v0
	v_mov_b32_e32 v4, v0
	v_mov_b32_e32 v5, v0
	v_mov_b32_e32 v6, v0
	v_mov_b32_e32 v7, v0
	v_mov_b32_e32 v16, v0
	v_mov_b32_e32 v17, v0
	v_mov_b32_e32 v18, v0
	v_mov_b32_e32 v19, v0
	v_mov_b32_e32 v20, v0
	v_mov_b32_e32 v21, v0
	v_mov_b32_e32 v22, v0
	v_mov_b32_e32 v23, v0
	v_mov_b32_e32 v32, v0
	v_mov_b32_e32 v33, v0
	v_mov_b32_e32 v34, v0
	v_mov_b32_e32 v35, v0
	v_mov_b32_e32 v36, v0
	v_mov_b32_e32 v37, v0
	v_mov_b32_e32 v38, v0
	v_mov_b32_e32 v39, v0
	v_mov_b32_e32 v48, v0
	v_mov_b32_e32 v49, v0
	v_mov_b32_e32 v50, v0
	v_mov_b32_e32 v51, v0
	v_mov_b32_e32 v52, v0
	v_mov_b32_e32 v53, v0
	v_mov_b32_e32 v54, v0
	v_mov_b32_e32 v55, v0
	v_mov_b32_e32 v8, v0
	v_mov_b32_e32 v9, v0
	v_mov_b32_e32 v10, v0
	v_mov_b32_e32 v11, v0
	v_mov_b32_e32 v12, v0
	v_mov_b32_e32 v13, v0
	v_mov_b32_e32 v14, v0
	v_mov_b32_e32 v15, v0
	v_mov_b32_e32 v24, v0
	v_mov_b32_e32 v25, v0
	v_mov_b32_e32 v26, v0
	v_mov_b32_e32 v27, v0
	v_mov_b32_e32 v28, v0
	v_mov_b32_e32 v29, v0
	v_mov_b32_e32 v30, v0
	v_mov_b32_e32 v31, v0
	v_mov_b32_e32 v40, v0
	v_mov_b32_e32 v41, v0
	v_mov_b32_e32 v42, v0
	v_mov_b32_e32 v43, v0
	v_mov_b32_e32 v44, v0
	v_mov_b32_e32 v45, v0
	v_mov_b32_e32 v46, v0
	v_mov_b32_e32 v47, v0
	v_mov_b32_e32 v56, v0
	v_mov_b32_e32 v57, v0
	v_mov_b32_e32 v58, v0
	v_mov_b32_e32 v59, v0
	v_mov_b32_e32 v60, v0
	v_mov_b32_e32 v61, v0
	v_mov_b32_e32 v62, v0
	v_mov_b32_e32 v63, v0
	v_mov_b32_e32 v64, v0
	v_mov_b32_e32 v65, v0
	v_mov_b32_e32 v66, v0
	v_mov_b32_e32 v67, v0
	v_mov_b32_e32 v68, v0
	v_mov_b32_e32 v69, v0
	v_mov_b32_e32 v70, v0
	v_mov_b32_e32 v71, v0
	v_mov_b32_e32 v80, v0
	v_mov_b32_e32 v81, v0
	v_mov_b32_e32 v82, v0
	v_mov_b32_e32 v83, v0
	v_mov_b32_e32 v84, v0
	v_mov_b32_e32 v85, v0
	v_mov_b32_e32 v86, v0
	v_mov_b32_e32 v87, v0
	v_mov_b32_e32 v98, v0
	v_mov_b32_e32 v99, v0
	v_mov_b32_e32 v100, v0
	v_mov_b32_e32 v101, v0
	v_mov_b32_e32 v102, v0
	v_mov_b32_e32 v103, v0
	v_mov_b32_e32 v104, v0
	v_mov_b32_e32 v105, v0
	v_mov_b32_e32 v114, v0
	v_mov_b32_e32 v115, v0
	v_mov_b32_e32 v116, v0
	v_mov_b32_e32 v117, v0
	v_mov_b32_e32 v118, v0
	v_mov_b32_e32 v119, v0
	v_mov_b32_e32 v120, v0
	v_mov_b32_e32 v121, v0
	v_mov_b32_e32 v72, v0
	v_mov_b32_e32 v73, v0
	v_mov_b32_e32 v74, v0
	v_mov_b32_e32 v75, v0
	v_mov_b32_e32 v76, v0
	v_mov_b32_e32 v77, v0
	v_mov_b32_e32 v78, v0
	v_mov_b32_e32 v79, v0
	v_mov_b32_e32 v88, v0
	v_mov_b32_e32 v89, v0
	v_mov_b32_e32 v90, v0
	v_mov_b32_e32 v91, v0
	v_mov_b32_e32 v92, v0
	v_mov_b32_e32 v93, v0
	v_mov_b32_e32 v94, v0
	v_mov_b32_e32 v95, v0
	v_mov_b32_e32 v106, v0
	v_mov_b32_e32 v107, v0
	v_mov_b32_e32 v108, v0
	v_mov_b32_e32 v109, v0
	v_mov_b32_e32 v110, v0
	v_mov_b32_e32 v111, v0
	v_mov_b32_e32 v112, v0
	v_mov_b32_e32 v113, v0
	v_mov_b32_e32 v122, v0
	v_mov_b32_e32 v123, v0
	v_mov_b32_e32 v124, v0
	v_mov_b32_e32 v125, v0
	v_mov_b32_e32 v126, v0
	v_mov_b32_e32 v127, v0
	v_mov_b32_e32 v128, v0
	v_mov_b32_e32 v129, v0
	.p2align 6

.LBB0_2131:
	s_add_i32 s17, s23, -2
	s_add_u32 s90, s26, 0x100
	v_mov_b32_e32 v0, 0
	s_addc_u32 s91, s27, 0
	s_mov_b32 s30, 0
	v_mov_b32_e32 v1, v0
	v_mov_b32_e32 v2, v0
	v_mov_b32_e32 v3, v0
	v_mov_b32_e32 v4, v0
	v_mov_b32_e32 v5, v0
	v_mov_b32_e32 v6, v0
	v_mov_b32_e32 v7, v0
	v_mov_b32_e32 v16, v0
	v_mov_b32_e32 v17, v0
	v_mov_b32_e32 v18, v0
	v_mov_b32_e32 v19, v0
	v_mov_b32_e32 v20, v0
	v_mov_b32_e32 v21, v0
	v_mov_b32_e32 v22, v0
	v_mov_b32_e32 v23, v0
	v_mov_b32_e32 v32, v0
	v_mov_b32_e32 v33, v0
	v_mov_b32_e32 v34, v0
	v_mov_b32_e32 v35, v0
	v_mov_b32_e32 v36, v0
	v_mov_b32_e32 v37, v0
	v_mov_b32_e32 v38, v0
	v_mov_b32_e32 v39, v0
	v_mov_b32_e32 v48, v0
	v_mov_b32_e32 v49, v0
	v_mov_b32_e32 v50, v0
	v_mov_b32_e32 v51, v0
	v_mov_b32_e32 v52, v0
	v_mov_b32_e32 v53, v0
	v_mov_b32_e32 v54, v0
	v_mov_b32_e32 v55, v0
	v_mov_b32_e32 v8, v0
	v_mov_b32_e32 v9, v0
	v_mov_b32_e32 v10, v0
	v_mov_b32_e32 v11, v0
	v_mov_b32_e32 v12, v0
	v_mov_b32_e32 v13, v0
	v_mov_b32_e32 v14, v0
	v_mov_b32_e32 v15, v0
	v_mov_b32_e32 v24, v0
	v_mov_b32_e32 v25, v0
	v_mov_b32_e32 v26, v0
	v_mov_b32_e32 v27, v0
	v_mov_b32_e32 v28, v0
	v_mov_b32_e32 v29, v0
	v_mov_b32_e32 v30, v0
	v_mov_b32_e32 v31, v0
	v_mov_b32_e32 v40, v0
	v_mov_b32_e32 v41, v0
	v_mov_b32_e32 v42, v0
	v_mov_b32_e32 v43, v0
	v_mov_b32_e32 v44, v0
	v_mov_b32_e32 v45, v0
	v_mov_b32_e32 v46, v0
	v_mov_b32_e32 v47, v0
	v_mov_b32_e32 v56, v0
	v_mov_b32_e32 v57, v0
	v_mov_b32_e32 v58, v0
	v_mov_b32_e32 v59, v0
	v_mov_b32_e32 v60, v0
	v_mov_b32_e32 v61, v0
	v_mov_b32_e32 v62, v0
	v_mov_b32_e32 v63, v0
	v_mov_b32_e32 v64, v0
	v_mov_b32_e32 v65, v0
	v_mov_b32_e32 v66, v0
	v_mov_b32_e32 v67, v0
	v_mov_b32_e32 v68, v0
	v_mov_b32_e32 v69, v0
	v_mov_b32_e32 v70, v0
	v_mov_b32_e32 v71, v0
	v_mov_b32_e32 v80, v0
	v_mov_b32_e32 v81, v0
	v_mov_b32_e32 v82, v0
	v_mov_b32_e32 v83, v0
	v_mov_b32_e32 v84, v0
	v_mov_b32_e32 v85, v0
	v_mov_b32_e32 v86, v0
	v_mov_b32_e32 v87, v0
	v_mov_b32_e32 v98, v0
	v_mov_b32_e32 v99, v0
	v_mov_b32_e32 v100, v0
	v_mov_b32_e32 v101, v0
	v_mov_b32_e32 v102, v0
	v_mov_b32_e32 v103, v0
	v_mov_b32_e32 v104, v0
	v_mov_b32_e32 v105, v0
	v_mov_b32_e32 v114, v0
	v_mov_b32_e32 v115, v0
	v_mov_b32_e32 v116, v0
	v_mov_b32_e32 v117, v0
	v_mov_b32_e32 v118, v0
	v_mov_b32_e32 v119, v0
	v_mov_b32_e32 v120, v0
	v_mov_b32_e32 v121, v0
	v_mov_b32_e32 v72, v0
	v_mov_b32_e32 v73, v0
	v_mov_b32_e32 v74, v0
	v_mov_b32_e32 v75, v0
	v_mov_b32_e32 v76, v0
	v_mov_b32_e32 v77, v0
	v_mov_b32_e32 v78, v0
	v_mov_b32_e32 v79, v0
	v_mov_b32_e32 v88, v0
	v_mov_b32_e32 v89, v0
	v_mov_b32_e32 v90, v0
	v_mov_b32_e32 v91, v0
	v_mov_b32_e32 v92, v0
	v_mov_b32_e32 v93, v0
	v_mov_b32_e32 v94, v0
	v_mov_b32_e32 v95, v0
	v_mov_b32_e32 v106, v0
	v_mov_b32_e32 v107, v0
	v_mov_b32_e32 v108, v0
	v_mov_b32_e32 v109, v0
	v_mov_b32_e32 v110, v0
	v_mov_b32_e32 v111, v0
	v_mov_b32_e32 v112, v0
	v_mov_b32_e32 v113, v0
	v_mov_b32_e32 v122, v0
	v_mov_b32_e32 v123, v0
	v_mov_b32_e32 v124, v0
	v_mov_b32_e32 v125, v0
	v_mov_b32_e32 v126, v0
	v_mov_b32_e32 v127, v0
	v_mov_b32_e32 v128, v0
	v_mov_b32_e32 v129, v0
	.p2align 6
